# phase 6 prologue: first two weight k-tiles requested before the selected-token list is waited for (two round trips overlap)
# baseline (speedup 1.0000x reference)
.Lgb5_done:
	s_or_b64 exec, exec, s[4:5]
	s_movk_i32 s12, 0xc0
	v_readlane_b32 s0, v245, 13
	s_barrier
	s_cmp_ge_i32 s0, s12
	s_cbranch_scc1 .LBB0_1366
	v_mov_b32_e32 v20, v187
	v_readlane_b32 s4, v245, 5
	v_readlane_b32 s5, v245, 6
	s_lshl_b32 s0, s85, 27
	v_lshrrev_b32_e32 v2, 3, v20
	v_and_b32_e32 v2, 7, v2
	v_and_b32_e32 v3, 0xc0, v20
	v_or_b32_e32 v178, v2, v3
	v_mov_b32_e32 v179, v1
	v_lshl_add_u64 v[2:3], v[178:179], 2, s[4:5]
	global_load_dword v162, v[2:3], off
	global_load_dword v163, v[2:3], off offset:32
	global_load_dword v164, v[2:3], off offset:64
	global_load_dword v165, v[2:3], off offset:96
	global_load_dword v166, v[2:3], off offset:128
	global_load_dword v167, v[2:3], off offset:160
	global_load_dword v168, v[2:3], off offset:192
	global_load_dword v169, v[2:3], off offset:224
	v_readlane_b32 s48, v247, 45
	v_readlane_b32 s49, v247, 46
	s_add_u32 s13, s48, s0
	s_addc_u32 s34, s49, 0
	v_readlane_b32 s4, v245, 7
	v_readlane_b32 s5, v245, 8
	s_add_u32 s0, s13, s4
	s_addc_u32 s4, s34, s5
	v_readlane_b32 s5, v245, 9
	s_add_u32 s6, s0, s5
	s_addc_u32 s7, s4, 0
	v_lshlrev_b32_e32 v4, 6, v20
	v_lshlrev_b32_e32 v5, 2, v20
	v_ashrrev_i32_e32 v23, 5, v20
	v_and_b32_e32 v4, 0x400, v4
	v_and_b32_e32 v2, 60, v5
	v_lshlrev_b32_e32 v5, 13, v23
	v_or3_b32 v190, v4, v5, v2
	v_mov_b32_e32 v191, v1
	v_lshlrev_b32_e32 v192, 2, v190
	s_movk_i32 s14, 0x4000
	v_bfe_u32 v197, v20, 5, 1
	v_and_b32_e32 v218, 0xffffffc0, v20
	v_lshlrev_b32_e32 v198, 1, v2
	v_and_b32_e32 v3, 31, v20
	v_cmp_gt_u32_e64 s[4:5], 16, v3
	v_cndmask_b32_e64 v4, 2, 0, s[4:5]
	v_lshlrev_b32_e32 v200, 1, v4
	v_readlane_b32 s35, v245, 16
	v_readlane_b32 s37, v245, 13
	s_lshl_b32 s0, s35, 1
	s_and_b32 s58, s0, 31
	s_lshl_b32 s58, s58, 18
	s_add_u32 s58, s6, s58
	s_addc_u32 s59, s7, 0
	s_add_u32 s60, s58, s33
	s_addc_u32 s61, s59, 0
	s_add_u32 s62, s58, s14
	s_addc_u32 s63, s59, 0
	s_add_u32 s64, s58, s97
	s_addc_u32 s65, s59, 0
	global_load_dwordx4 v[130:133], v192, s[58:59]
	global_load_dwordx4 v[134:137], v192, s[60:61]
	global_load_dwordx4 v[138:141], v192, s[62:63]
	global_load_dwordx4 v[142:145], v192, s[64:65]
	s_add_i32 s0, s0, 1
	s_and_b32 s58, s0, 31
	s_lshl_b32 s58, s58, 18
	s_add_u32 s58, s6, s58
	s_addc_u32 s59, s7, 0
	s_add_u32 s60, s58, s33
	s_addc_u32 s61, s59, 0
	s_add_u32 s62, s58, s14
	s_addc_u32 s63, s59, 0
	s_add_u32 s64, s58, s97
	s_addc_u32 s65, s59, 0
	global_load_dwordx4 v[146:149], v192, s[58:59]
	global_load_dwordx4 v[150:153], v192, s[60:61]
	global_load_dwordx4 v[154:157], v192, s[62:63]
	global_load_dwordx4 v[158:161], v192, s[64:65]
	v_readfirstlane_b32 s53, v20
	s_and_b32 s53, s53, 0xc0
	s_lshl_b32 s53, s53, 8
	s_movk_i32 s54, 0x2000
	v_lshrrev_b32_e32 v4, 1, v3
	v_and_b32_e32 v4, 7, v4
	v_xor_b32_e32 v4, v4, v197
	v_lshlrev_b32_e32 v4, 4, v4
	v_lshl_or_b32 v4, v3, 7, v4
	v_or_b32_e32 v216, s53, v4
	v_xor_b32_e32 v0, 32, v216
	v_xor_b32_e32 v180, 64, v216
	v_xor_b32_e32 v194, 0x60, v216
	v_lshrrev_b32_e32 v4, 2, v3
	v_and_b32_e32 v4, 3, v4
	v_xor_b32_e32 v5, v4, v197
	v_lshlrev_b32_e32 v5, 4, v5
	v_lshl_or_b32 v5, v3, 6, v5
	v_add_u32_e32 v217, 0x10000, v5
	v_xor_b32_e32 v209, 32, v217
	v_lshrrev_b32_e32 v5, 1, v23
	v_xor_b32_e32 v5, v5, v4
	v_lshlrev_b32_e32 v5, 4, v5
	v_and_b32_e32 v6, 1, v23
	v_lshl_or_b32 v5, v6, 3, v5
	v_lshl_or_b32 v5, v3, 6, v5
	v_add_u32_e32 v219, 0x10000, v5
	v_and_b32_e32 v4, 7, v20
	v_bfe_u32 v5, v20, 4, 2
	v_xor_b32_e32 v4, v4, v5
	v_lshlrev_b32_e32 v196, 4, v4
	v_xor_b32_e32 v215, 64, v196
	s_add_u32 s56, s22, 0xfffff000
	s_addc_u32 s57, s23, -1
	s_waitcnt vmcnt(8)
	v_lshl_add_u32 v162, v162, 11, v196
	v_lshl_add_u32 v163, v163, 11, v215
	v_lshl_add_u32 v164, v164, 11, v196
	v_lshl_add_u32 v165, v165, 11, v215
	v_lshl_add_u32 v166, v166, 11, v196
	v_lshl_add_u32 v167, v167, 11, v215
	v_lshl_add_u32 v168, v168, 11, v196
	v_lshl_add_u32 v169, v169, 11, v215
	v_add_u32_e32 v162, 0x1000, v162
	v_add_u32_e32 v163, 0xc00, v163
	v_add_u32_e32 v164, 0x800, v164
	v_add_u32_e32 v165, 0x400, v165
	v_add_u32_e32 v166, 0x1000, v166
	v_add_u32_e32 v167, 0xc00, v167
	v_add_u32_e32 v168, 0x800, v168
	v_add_u32_e32 v169, 0x400, v169
	s_lshl_b32 s0, s35, 1
	s_and_b32 s40, s0, 30
	s_lshl_b32 s40, s40, 6
	s_add_u32 s40, s56, s40
	s_addc_u32 s41, s57, 0
	s_mov_b32 m0, s53
	s_nop 0
	global_load_lds_dwordx4 v162, s[40:41]
	global_load_lds_dwordx4 v163, s[40:41] offset:1024
	global_load_lds_dwordx4 v164, s[40:41] offset:2048
	global_load_lds_dwordx4 v165, s[40:41] offset:3072
	s_add_u32 m0, m0, 0x1000
	s_nop 0
	global_load_lds_dwordx4 v166, s[40:41]
	global_load_lds_dwordx4 v167, s[40:41] offset:1024
	global_load_lds_dwordx4 v168, s[40:41] offset:2048
	global_load_lds_dwordx4 v169, s[40:41] offset:3072
	s_waitcnt vmcnt(12)
	v_cvt_pk_bf16_f32 v202, v130, v134
	v_cvt_pk_bf16_f32 v203, v138, v142
	v_cvt_pk_bf16_f32 v204, v131, v135
	v_cvt_pk_bf16_f32 v205, v139, v143
	ds_write2st64_b64 v219, v[202:203], v[204:205] offset0:0 offset1:4
	v_cvt_pk_bf16_f32 v206, v132, v136
	v_cvt_pk_bf16_f32 v207, v140, v144
	v_cvt_pk_bf16_f32 v202, v133, v137
	v_cvt_pk_bf16_f32 v203, v141, v145
	ds_write2st64_b64 v219, v[206:207], v[202:203] offset0:8 offset1:12
	s_add_i32 s0, s0, 2
	s_and_b32 s58, s0, 31
	s_lshl_b32 s58, s58, 18
	s_add_u32 s58, s6, s58
	s_addc_u32 s59, s7, 0
	s_add_u32 s60, s58, s33
	s_addc_u32 s61, s59, 0
	s_add_u32 s62, s58, s14
	s_addc_u32 s63, s59, 0
	s_add_u32 s64, s58, s97
	s_addc_u32 s65, s59, 0
	global_load_dwordx4 v[130:133], v192, s[58:59]
	global_load_dwordx4 v[134:137], v192, s[60:61]
	global_load_dwordx4 v[138:141], v192, s[62:63]
	global_load_dwordx4 v[142:145], v192, s[64:65]
	s_waitcnt vmcnt(4)
	ds_read_b128 v[220:223], v216
	ds_read_b128 v[224:227], v216 offset:4096
	s_branch .LBB0_1358
